# baseline instruction stream plus compute-dtype header comment only (restructuring experiments on the GEMM sync did not beat it)
# speedup vs baseline: 1.0024x; 1.0024x over previous
.LBB0_215:
	s_add_u32 s14, s12, 0xfff80080
	s_addc_u32 s15, s13, -1
	s_add_i32 s67, 0, 0x10000
	s_cmp_eq_u32 s53, 28
	s_cselect_b32 s17, s39, s15
	s_cselect_b32 s16, s47, s14
	v_add_u32_e32 v144, s67, v185
	s_cselect_b32 s15, s31, s52
	s_cselect_b32 s14, s48, s49
	s_add_i32 s82, 0, 0x14000
	ds_read_b128 v[88:91], v144
	ds_read_b128 v[92:95], v144 offset:1024
	ds_read_b128 v[158:161], v144 offset:2048
	ds_read_b128 v[162:165], v144 offset:3072
	v_add_u32_e32 v144, s82, v185
	ds_read_b128 v[166:169], v144
	ds_read_b128 v[188:191], v144 offset:1024
	ds_read_b128 v[192:195], v144 offset:2048
	ds_read_b128 v[196:199], v144 offset:3072
	v_lshl_add_u64 v[170:171], s[12:13], 0, v[154:155]
	s_add_i32 m0, s9, 0xc000
	ds_read_b128 v[200:203], v187
	ds_read_b128 v[204:207], v187 offset:1024
	ds_read_b128 v[208:211], v187 offset:2048
	ds_read_b128 v[212:215], v187 offset:3072
	ds_read_b128 v[216:219], v187 offset:4096
	ds_read_b128 v[220:223], v187 offset:5120
	ds_read_b128 v[224:227], v187 offset:6144
	ds_read_b128 v[228:231], v187 offset:7168
	global_load_lds_dwordx4 v[170:171], off
	v_lshl_add_u64 v[170:171], s[12:13], 0, v[156:157]
	s_add_i32 m0, s9, 0xe000
	s_nop 0
	global_load_lds_dwordx4 v[170:171], off
	s_waitcnt vmcnt(8)
	s_waitcnt lgkmcnt(0)
	s_barrier
	s_setprio 1
	s_waitcnt lgkmcnt(0)
	v_mfma_f32_16x16x32_bf16 v[132:135], v[88:91], v[200:203], v[132:135]
	v_mfma_f32_16x16x32_bf16 v[128:131], v[158:161], v[200:203], v[128:131]
	v_mfma_f32_16x16x32_bf16 v[124:127], v[88:91], v[208:211], v[124:127]
	v_mfma_f32_16x16x32_bf16 v[120:123], v[158:161], v[208:211], v[120:123]
	v_mfma_f32_16x16x32_bf16 v[116:119], v[88:91], v[216:219], v[116:119]
	v_mfma_f32_16x16x32_bf16 v[112:115], v[158:161], v[216:219], v[112:115]
	v_mfma_f32_16x16x32_bf16 v[108:111], v[88:91], v[224:227], v[108:111]
	v_mfma_f32_16x16x32_bf16 v[104:107], v[158:161], v[224:227], v[104:107]
	v_mfma_f32_16x16x32_bf16 v[132:135], v[92:95], v[204:207], v[132:135]
	v_mfma_f32_16x16x32_bf16 v[128:131], v[162:165], v[204:207], v[128:131]
	v_mfma_f32_16x16x32_bf16 v[124:127], v[92:95], v[212:215], v[124:127]
	v_mfma_f32_16x16x32_bf16 v[120:123], v[162:165], v[212:215], v[120:123]
	v_mfma_f32_16x16x32_bf16 v[116:119], v[92:95], v[220:223], v[116:119]
	v_mfma_f32_16x16x32_bf16 v[112:115], v[162:165], v[220:223], v[112:115]
	v_mfma_f32_16x16x32_bf16 v[108:111], v[92:95], v[228:231], v[108:111]
	v_mfma_f32_16x16x32_bf16 v[104:107], v[162:165], v[228:231], v[104:107]
	s_setprio 0
	s_setprio 1
	v_mfma_f32_16x16x32_bf16 v[60:63], v[166:169], v[200:203], v[60:63]
	v_mfma_f32_16x16x32_bf16 v[56:59], v[192:195], v[200:203], v[56:59]
	v_mfma_f32_16x16x32_bf16 v[52:55], v[166:169], v[208:211], v[52:55]
	v_mfma_f32_16x16x32_bf16 v[48:51], v[192:195], v[208:211], v[48:51]
	v_mfma_f32_16x16x32_bf16 v[44:47], v[166:169], v[216:219], v[44:47]
	v_mfma_f32_16x16x32_bf16 v[40:43], v[192:195], v[216:219], v[40:43]
	v_mfma_f32_16x16x32_bf16 v[36:39], v[166:169], v[224:227], v[36:39]
	v_mfma_f32_16x16x32_bf16 v[32:35], v[192:195], v[224:227], v[32:35]
	v_mfma_f32_16x16x32_bf16 v[60:63], v[188:191], v[204:207], v[60:63]
	v_mfma_f32_16x16x32_bf16 v[56:59], v[196:199], v[204:207], v[56:59]
	v_mfma_f32_16x16x32_bf16 v[52:55], v[188:191], v[212:215], v[52:55]
	v_mfma_f32_16x16x32_bf16 v[48:51], v[196:199], v[212:215], v[48:51]
	v_mfma_f32_16x16x32_bf16 v[44:47], v[188:191], v[220:223], v[44:47]
	v_mfma_f32_16x16x32_bf16 v[40:43], v[196:199], v[220:223], v[40:43]
	v_mfma_f32_16x16x32_bf16 v[36:39], v[188:191], v[228:231], v[36:39]
	v_mfma_f32_16x16x32_bf16 v[32:35], v[196:199], v[228:231], v[32:35]
	s_setprio 0
	s_barrier
	s_add_i32 s67, s67, s8
	v_lshl_add_u64 v[170:171], s[14:15], 0, v[140:141]
	s_mov_b32 m0, s67
	ds_read_b128 v[200:203], v187 offset:16384
	ds_read_b128 v[204:207], v187 offset:17408
	ds_read_b128 v[208:211], v187 offset:18432
	ds_read_b128 v[212:215], v187 offset:19456
	ds_read_b128 v[216:219], v187 offset:20480
	ds_read_b128 v[220:223], v187 offset:21504
	ds_read_b128 v[224:227], v187 offset:22528
	ds_read_b128 v[228:231], v187 offset:23552
	global_load_lds_dwordx4 v[170:171], off
	s_add_i32 m0, s67, 0x2000
	s_add_u32 s80, s14, 0x80000
	v_lshl_add_u64 v[232:233], s[14:15], 0, v[136:137]
	s_addc_u32 s81, s15, 0
	s_add_i32 s67, s82, s8
	global_load_lds_dwordx4 v[232:233], off
	v_lshl_add_u64 v[234:235], s[80:81], 0, v[140:141]
	s_mov_b32 m0, s67
	v_lshl_add_u64 v[236:237], s[16:17], 0, v[138:139]
	global_load_lds_dwordx4 v[234:235], off
	v_lshl_add_u64 v[234:235], s[80:81], 0, v[136:137]
	s_add_i32 m0, s67, 0x2000
	s_nop 0
	global_load_lds_dwordx4 v[234:235], off
	v_lshl_add_u64 v[234:235], s[16:17], 0, v[142:143]
	s_mov_b32 m0, s9
	s_nop 0
	global_load_lds_dwordx4 v[234:235], off
	s_mov_b32 m0, s35
	s_nop 0
	global_load_lds_dwordx4 v[236:237], off
	s_waitcnt vmcnt(8)
	s_waitcnt lgkmcnt(0)
	s_barrier
	s_setprio 1
	s_waitcnt lgkmcnt(0)
	v_mfma_f32_16x16x32_bf16 v[100:103], v[88:91], v[200:203], v[100:103]
	v_mfma_f32_16x16x32_bf16 v[96:99], v[158:161], v[200:203], v[96:99]
	v_mfma_f32_16x16x32_bf16 v[84:87], v[88:91], v[208:211], v[84:87]
	v_mfma_f32_16x16x32_bf16 v[80:83], v[158:161], v[208:211], v[80:83]
	v_mfma_f32_16x16x32_bf16 v[76:79], v[88:91], v[216:219], v[76:79]
	v_mfma_f32_16x16x32_bf16 v[72:75], v[158:161], v[216:219], v[72:75]
	v_mfma_f32_16x16x32_bf16 v[68:71], v[88:91], v[224:227], v[68:71]
	v_mfma_f32_16x16x32_bf16 v[64:67], v[158:161], v[224:227], v[64:67]
	v_mfma_f32_16x16x32_bf16 v[100:103], v[92:95], v[204:207], v[100:103]
	v_mfma_f32_16x16x32_bf16 v[96:99], v[162:165], v[204:207], v[96:99]
	v_mfma_f32_16x16x32_bf16 v[84:87], v[92:95], v[212:215], v[84:87]
	v_mfma_f32_16x16x32_bf16 v[80:83], v[162:165], v[212:215], v[80:83]
	v_mfma_f32_16x16x32_bf16 v[76:79], v[92:95], v[220:223], v[76:79]
	v_mfma_f32_16x16x32_bf16 v[72:75], v[162:165], v[220:223], v[72:75]
	v_mfma_f32_16x16x32_bf16 v[68:71], v[92:95], v[228:231], v[68:71]
	v_mfma_f32_16x16x32_bf16 v[64:67], v[162:165], v[228:231], v[64:67]
	s_setprio 0
	s_setprio 1
	v_mfma_f32_16x16x32_bf16 v[28:31], v[166:169], v[200:203], v[28:31]
	v_mfma_f32_16x16x32_bf16 v[24:27], v[192:195], v[200:203], v[24:27]
	v_mfma_f32_16x16x32_bf16 v[20:23], v[166:169], v[208:211], v[20:23]
	v_mfma_f32_16x16x32_bf16 v[16:19], v[192:195], v[208:211], v[16:19]
	v_mfma_f32_16x16x32_bf16 v[12:15], v[166:169], v[216:219], v[12:15]
	v_mfma_f32_16x16x32_bf16 v[8:11], v[192:195], v[216:219], v[8:11]
	v_mfma_f32_16x16x32_bf16 v[4:7], v[166:169], v[224:227], v[4:7]
	v_mfma_f32_16x16x32_bf16 v[0:3], v[192:195], v[224:227], v[0:3]
	v_mfma_f32_16x16x32_bf16 v[28:31], v[188:191], v[204:207], v[28:31]
	v_mfma_f32_16x16x32_bf16 v[24:27], v[196:199], v[204:207], v[24:27]
	v_mfma_f32_16x16x32_bf16 v[20:23], v[188:191], v[212:215], v[20:23]
	v_mfma_f32_16x16x32_bf16 v[16:19], v[196:199], v[212:215], v[16:19]
	v_mfma_f32_16x16x32_bf16 v[12:15], v[188:191], v[220:223], v[12:15]
	v_mfma_f32_16x16x32_bf16 v[8:11], v[196:199], v[220:223], v[8:11]
	v_mfma_f32_16x16x32_bf16 v[4:7], v[188:191], v[228:231], v[4:7]
	v_mfma_f32_16x16x32_bf16 v[0:3], v[196:199], v[228:231], v[0:3]
	s_setprio 0
	s_barrier
	s_add_i32 s67, 0, 0x18000
	v_add_u32_e32 v144, s67, v185
	s_add_i32 s80, 0, 0x1c000
	ds_read_b128 v[88:91], v144
	ds_read_b128 v[92:95], v144 offset:1024
	ds_read_b128 v[158:161], v144 offset:2048
	ds_read_b128 v[162:165], v144 offset:3072
	v_add_u32_e32 v144, s80, v185
	ds_read_b128 v[166:169], v144
	ds_read_b128 v[188:191], v144 offset:1024
	ds_read_b128 v[192:195], v144 offset:2048
	ds_read_b128 v[196:199], v144 offset:3072
	s_add_u32 s16, s16, 0x80000
	s_addc_u32 s17, s17, 0
	s_mov_b32 m0, s5
	v_lshl_add_u64 v[238:239], s[16:17], 0, v[142:143]
	ds_read_b128 v[200:203], v187 offset:32768
	ds_read_b128 v[204:207], v187 offset:33792
	ds_read_b128 v[208:211], v187 offset:34816
	ds_read_b128 v[212:215], v187 offset:35840
	ds_read_b128 v[216:219], v187 offset:36864
	ds_read_b128 v[220:223], v187 offset:37888
	ds_read_b128 v[224:227], v187 offset:38912
	ds_read_b128 v[228:231], v187 offset:39936
	global_load_lds_dwordx4 v[238:239], off
	v_lshl_add_u64 v[238:239], s[16:17], 0, v[138:139]
	s_mov_b32 m0, s26
	s_nop 0
	global_load_lds_dwordx4 v[238:239], off
	s_waitcnt vmcnt(8)
	s_waitcnt lgkmcnt(0)
	s_barrier
	s_setprio 1
	s_waitcnt lgkmcnt(0)
	v_mfma_f32_16x16x32_bf16 v[132:135], v[88:91], v[200:203], v[132:135]
	v_mfma_f32_16x16x32_bf16 v[128:131], v[158:161], v[200:203], v[128:131]
	v_mfma_f32_16x16x32_bf16 v[124:127], v[88:91], v[208:211], v[124:127]
	v_mfma_f32_16x16x32_bf16 v[120:123], v[158:161], v[208:211], v[120:123]
	v_mfma_f32_16x16x32_bf16 v[116:119], v[88:91], v[216:219], v[116:119]
	v_mfma_f32_16x16x32_bf16 v[112:115], v[158:161], v[216:219], v[112:115]
	v_mfma_f32_16x16x32_bf16 v[108:111], v[88:91], v[224:227], v[108:111]
	v_mfma_f32_16x16x32_bf16 v[104:107], v[158:161], v[224:227], v[104:107]
	v_mfma_f32_16x16x32_bf16 v[132:135], v[92:95], v[204:207], v[132:135]
	v_mfma_f32_16x16x32_bf16 v[128:131], v[162:165], v[204:207], v[128:131]
	v_mfma_f32_16x16x32_bf16 v[124:127], v[92:95], v[212:215], v[124:127]
	v_mfma_f32_16x16x32_bf16 v[120:123], v[162:165], v[212:215], v[120:123]
	v_mfma_f32_16x16x32_bf16 v[116:119], v[92:95], v[220:223], v[116:119]
	v_mfma_f32_16x16x32_bf16 v[112:115], v[162:165], v[220:223], v[112:115]
	v_mfma_f32_16x16x32_bf16 v[108:111], v[92:95], v[228:231], v[108:111]
	v_mfma_f32_16x16x32_bf16 v[104:107], v[162:165], v[228:231], v[104:107]
	s_setprio 0
	s_setprio 1
	v_mfma_f32_16x16x32_bf16 v[60:63], v[166:169], v[200:203], v[60:63]
	v_mfma_f32_16x16x32_bf16 v[56:59], v[192:195], v[200:203], v[56:59]
	v_mfma_f32_16x16x32_bf16 v[52:55], v[166:169], v[208:211], v[52:55]
	v_mfma_f32_16x16x32_bf16 v[48:51], v[192:195], v[208:211], v[48:51]
	v_mfma_f32_16x16x32_bf16 v[44:47], v[166:169], v[216:219], v[44:47]
	v_mfma_f32_16x16x32_bf16 v[40:43], v[192:195], v[216:219], v[40:43]
	v_mfma_f32_16x16x32_bf16 v[36:39], v[166:169], v[224:227], v[36:39]
	v_mfma_f32_16x16x32_bf16 v[32:35], v[192:195], v[224:227], v[32:35]
	v_mfma_f32_16x16x32_bf16 v[60:63], v[188:191], v[204:207], v[60:63]
	v_mfma_f32_16x16x32_bf16 v[56:59], v[196:199], v[204:207], v[56:59]
	v_mfma_f32_16x16x32_bf16 v[52:55], v[188:191], v[212:215], v[52:55]
	v_mfma_f32_16x16x32_bf16 v[48:51], v[196:199], v[212:215], v[48:51]
	v_mfma_f32_16x16x32_bf16 v[44:47], v[188:191], v[220:223], v[44:47]
	v_mfma_f32_16x16x32_bf16 v[40:43], v[196:199], v[220:223], v[40:43]
	v_mfma_f32_16x16x32_bf16 v[36:39], v[188:191], v[228:231], v[36:39]
	v_mfma_f32_16x16x32_bf16 v[32:35], v[196:199], v[228:231], v[32:35]
	s_setprio 0
	s_barrier
	s_add_i32 s16, s67, s8
	v_lshl_add_u64 v[170:171], v[170:171], 0, s[68:69]
	s_mov_b32 m0, s16
	ds_read_b128 v[200:203], v187 offset:49152
	ds_read_b128 v[204:207], v187 offset:50176
	ds_read_b128 v[208:211], v187 offset:51200
	ds_read_b128 v[212:215], v187 offset:52224
	ds_read_b128 v[216:219], v187 offset:53248
	ds_read_b128 v[220:223], v187 offset:54272
	ds_read_b128 v[224:227], v187 offset:55296
	ds_read_b128 v[228:231], v187 offset:56320
	global_load_lds_dwordx4 v[170:171], off
	s_add_i32 m0, s16, 0x2000
	s_add_u32 s14, s14, 0x80080
	v_lshl_add_u64 v[170:171], v[232:233], 0, s[68:69]
	s_addc_u32 s15, s15, 0
	s_add_i32 s16, s80, s8
	global_load_lds_dwordx4 v[170:171], off
	v_lshl_add_u64 v[170:171], s[14:15], 0, v[140:141]
	s_mov_b32 m0, s16
	s_nop 0
	global_load_lds_dwordx4 v[170:171], off
	v_lshl_add_u64 v[170:171], s[14:15], 0, v[136:137]
	s_add_i32 m0, s16, 0x2000
	s_nop 0
	global_load_lds_dwordx4 v[170:171], off
	v_lshl_add_u64 v[170:171], v[234:235], 0, s[68:69]
	s_mov_b32 m0, s4
	s_nop 0
	global_load_lds_dwordx4 v[170:171], off
	v_lshl_add_u64 v[170:171], v[236:237], 0, s[68:69]
	s_mov_b32 m0, s70
	s_nop 0
	global_load_lds_dwordx4 v[170:171], off
	s_waitcnt vmcnt(8)
	s_waitcnt lgkmcnt(0)
	s_barrier
	s_setprio 1
	s_waitcnt lgkmcnt(0)
	v_mfma_f32_16x16x32_bf16 v[100:103], v[88:91], v[200:203], v[100:103]
	v_mfma_f32_16x16x32_bf16 v[96:99], v[158:161], v[200:203], v[96:99]
	v_mfma_f32_16x16x32_bf16 v[84:87], v[88:91], v[208:211], v[84:87]
	v_mfma_f32_16x16x32_bf16 v[80:83], v[158:161], v[208:211], v[80:83]
	v_mfma_f32_16x16x32_bf16 v[76:79], v[88:91], v[216:219], v[76:79]
	v_mfma_f32_16x16x32_bf16 v[72:75], v[158:161], v[216:219], v[72:75]
	v_mfma_f32_16x16x32_bf16 v[68:71], v[88:91], v[224:227], v[68:71]
	v_mfma_f32_16x16x32_bf16 v[64:67], v[158:161], v[224:227], v[64:67]
	v_mfma_f32_16x16x32_bf16 v[100:103], v[92:95], v[204:207], v[100:103]
	v_mfma_f32_16x16x32_bf16 v[96:99], v[162:165], v[204:207], v[96:99]
	v_mfma_f32_16x16x32_bf16 v[84:87], v[92:95], v[212:215], v[84:87]
	v_mfma_f32_16x16x32_bf16 v[80:83], v[162:165], v[212:215], v[80:83]
	v_mfma_f32_16x16x32_bf16 v[76:79], v[92:95], v[220:223], v[76:79]
	v_mfma_f32_16x16x32_bf16 v[72:75], v[162:165], v[220:223], v[72:75]
	v_mfma_f32_16x16x32_bf16 v[68:71], v[92:95], v[228:231], v[68:71]
	v_mfma_f32_16x16x32_bf16 v[64:67], v[162:165], v[228:231], v[64:67]
	s_setprio 0
	s_setprio 1
	v_mfma_f32_16x16x32_bf16 v[28:31], v[166:169], v[200:203], v[28:31]
	v_mfma_f32_16x16x32_bf16 v[24:27], v[192:195], v[200:203], v[24:27]
	v_mfma_f32_16x16x32_bf16 v[20:23], v[166:169], v[208:211], v[20:23]
	v_mfma_f32_16x16x32_bf16 v[16:19], v[192:195], v[208:211], v[16:19]
	v_mfma_f32_16x16x32_bf16 v[12:15], v[166:169], v[216:219], v[12:15]
	v_mfma_f32_16x16x32_bf16 v[8:11], v[192:195], v[216:219], v[8:11]
	v_mfma_f32_16x16x32_bf16 v[4:7], v[166:169], v[224:227], v[4:7]
	v_mfma_f32_16x16x32_bf16 v[0:3], v[192:195], v[224:227], v[0:3]
	v_mfma_f32_16x16x32_bf16 v[28:31], v[188:191], v[204:207], v[28:31]
	v_mfma_f32_16x16x32_bf16 v[24:27], v[196:199], v[204:207], v[24:27]
	v_mfma_f32_16x16x32_bf16 v[20:23], v[188:191], v[212:215], v[20:23]
	v_mfma_f32_16x16x32_bf16 v[16:19], v[196:199], v[212:215], v[16:19]
	v_mfma_f32_16x16x32_bf16 v[12:15], v[188:191], v[220:223], v[12:15]
	v_mfma_f32_16x16x32_bf16 v[8:11], v[196:199], v[220:223], v[8:11]
	v_mfma_f32_16x16x32_bf16 v[4:7], v[188:191], v[228:231], v[4:7]
	v_mfma_f32_16x16x32_bf16 v[0:3], v[196:199], v[228:231], v[0:3]
	s_setprio 0
	s_barrier
	s_add_i32 s53, s53, 2
	s_add_u32 s12, s12, 0x100
	s_addc_u32 s13, s13, 0
	s_add_u32 s49, s49, 0x100
	s_addc_u32 s52, s52, 0
	s_cmp_gt_u32 s53, 29
	s_cbranch_scc0 .LBB0_215
	s_and_b64 vcc, exec, s[28:29]
	s_cbranch_vccz .LBB0_218
	s_barrier

.LBB0_785:
	s_add_u32 s14, s12, 0xfff80080
	s_addc_u32 s15, s13, -1
	s_add_i32 s86, 0, 0x10000
	s_cmp_eq_u32 s1, s85
	s_cselect_b32 s51, s47, s15
	s_cselect_b32 s50, s67, s14
	s_cselect_b32 s15, s80, s84
	s_cselect_b32 s14, s81, s83
	s_add_i32 s96, 0, 0x14000
	v_add_u32_e32 v140, s86, v186
	v_add_u32_e32 v144, s96, v186
	ds_read_b128 v[128:131], v140
	ds_read_b128 v[132:135], v140 offset:1024
	ds_read_b128 v[136:139], v140 offset:2048
	ds_read_b128 v[140:143], v140 offset:3072
	ds_read_b128 v[164:167], v144
	ds_read_b128 v[168:171], v144 offset:1024
	ds_read_b128 v[190:193], v144 offset:2048
	ds_read_b128 v[194:197], v144 offset:3072
	v_lshl_add_u64 v[230:231], s[12:13], 0, v[160:161]
	s_add_i32 m0, s5, 0xc000
	ds_read_b128 v[198:201], v188
	ds_read_b128 v[202:205], v188 offset:1024
	ds_read_b128 v[206:209], v188 offset:2048
	ds_read_b128 v[210:213], v188 offset:3072
	ds_read_b128 v[214:217], v188 offset:4096
	ds_read_b128 v[218:221], v188 offset:5120
	ds_read_b128 v[222:225], v188 offset:6144
	ds_read_b128 v[226:229], v188 offset:7168
	global_load_lds_dwordx4 v[230:231], off
	v_lshl_add_u64 v[230:231], s[12:13], 0, v[162:163]
	s_add_i32 m0, s5, 0xe000
	s_nop 0
	global_load_lds_dwordx4 v[230:231], off
	s_waitcnt vmcnt(8)
	s_waitcnt lgkmcnt(0)
	s_barrier
	s_setprio 1
	s_waitcnt lgkmcnt(0)
	v_mfma_f32_16x16x32_bf16 v[124:127], v[128:131], v[198:201], v[124:127]
	v_mfma_f32_16x16x32_bf16 v[120:123], v[136:139], v[198:201], v[120:123]
	v_mfma_f32_16x16x32_bf16 v[116:119], v[128:131], v[206:209], v[116:119]
	v_mfma_f32_16x16x32_bf16 v[112:115], v[136:139], v[206:209], v[112:115]
	v_mfma_f32_16x16x32_bf16 v[108:111], v[128:131], v[214:217], v[108:111]
	v_mfma_f32_16x16x32_bf16 v[104:107], v[136:139], v[214:217], v[104:107]
	v_mfma_f32_16x16x32_bf16 v[100:103], v[128:131], v[222:225], v[100:103]
	v_mfma_f32_16x16x32_bf16 v[96:99], v[136:139], v[222:225], v[96:99]
	v_mfma_f32_16x16x32_bf16 v[124:127], v[132:135], v[202:205], v[124:127]
	v_mfma_f32_16x16x32_bf16 v[120:123], v[140:143], v[202:205], v[120:123]
	v_mfma_f32_16x16x32_bf16 v[116:119], v[132:135], v[210:213], v[116:119]
	v_mfma_f32_16x16x32_bf16 v[112:115], v[140:143], v[210:213], v[112:115]
	v_mfma_f32_16x16x32_bf16 v[108:111], v[132:135], v[218:221], v[108:111]
	v_mfma_f32_16x16x32_bf16 v[104:107], v[140:143], v[218:221], v[104:107]
	v_mfma_f32_16x16x32_bf16 v[100:103], v[132:135], v[226:229], v[100:103]
	v_mfma_f32_16x16x32_bf16 v[96:99], v[140:143], v[226:229], v[96:99]
	s_setprio 0
	s_setprio 1
	v_mfma_f32_16x16x32_bf16 v[60:63], v[164:167], v[198:201], v[60:63]
	v_mfma_f32_16x16x32_bf16 v[56:59], v[190:193], v[198:201], v[56:59]
	v_mfma_f32_16x16x32_bf16 v[52:55], v[164:167], v[206:209], v[52:55]
	v_mfma_f32_16x16x32_bf16 v[48:51], v[190:193], v[206:209], v[48:51]
	v_mfma_f32_16x16x32_bf16 v[44:47], v[164:167], v[214:217], v[44:47]
	v_mfma_f32_16x16x32_bf16 v[40:43], v[190:193], v[214:217], v[40:43]
	v_mfma_f32_16x16x32_bf16 v[36:39], v[164:167], v[222:225], v[36:39]
	v_mfma_f32_16x16x32_bf16 v[32:35], v[190:193], v[222:225], v[32:35]
	v_mfma_f32_16x16x32_bf16 v[60:63], v[168:171], v[202:205], v[60:63]
	v_mfma_f32_16x16x32_bf16 v[56:59], v[194:197], v[202:205], v[56:59]
	v_mfma_f32_16x16x32_bf16 v[52:55], v[168:171], v[210:213], v[52:55]
	v_mfma_f32_16x16x32_bf16 v[48:51], v[194:197], v[210:213], v[48:51]
	v_mfma_f32_16x16x32_bf16 v[44:47], v[168:171], v[218:221], v[44:47]
	v_mfma_f32_16x16x32_bf16 v[40:43], v[194:197], v[218:221], v[40:43]
	v_mfma_f32_16x16x32_bf16 v[36:39], v[168:171], v[226:229], v[36:39]
	v_mfma_f32_16x16x32_bf16 v[32:35], v[194:197], v[226:229], v[32:35]
	s_setprio 0
	s_barrier
	s_add_i32 s86, s86, s4
	v_lshl_add_u64 v[230:231], s[14:15], 0, v[156:157]
	s_mov_b32 m0, s86
	ds_read_b128 v[198:201], v188 offset:16384
	ds_read_b128 v[202:205], v188 offset:17408
	ds_read_b128 v[206:209], v188 offset:18432
	ds_read_b128 v[210:213], v188 offset:19456
	ds_read_b128 v[214:217], v188 offset:20480
	ds_read_b128 v[218:221], v188 offset:21504
	ds_read_b128 v[222:225], v188 offset:22528
	ds_read_b128 v[226:229], v188 offset:23552
	global_load_lds_dwordx4 v[230:231], off
	s_add_i32 m0, s86, 0x2000
	s_add_u32 s86, s14, 0x80000
	v_lshl_add_u64 v[232:233], s[14:15], 0, v[152:153]
	s_addc_u32 s87, s15, 0
	s_add_i32 s96, s96, s4
	global_load_lds_dwordx4 v[232:233], off
	v_lshl_add_u64 v[234:235], s[86:87], 0, v[156:157]
	s_mov_b32 m0, s96
	v_lshl_add_u64 v[236:237], s[50:51], 0, v[154:155]
	global_load_lds_dwordx4 v[234:235], off
	v_lshl_add_u64 v[234:235], s[86:87], 0, v[152:153]
	s_add_i32 m0, s96, 0x2000
	s_nop 0
	global_load_lds_dwordx4 v[234:235], off
	v_lshl_add_u64 v[234:235], s[50:51], 0, v[158:159]
	s_mov_b32 m0, s5
	s_nop 0
	global_load_lds_dwordx4 v[234:235], off
	s_mov_b32 m0, s8
	s_nop 0
	global_load_lds_dwordx4 v[236:237], off
	s_waitcnt vmcnt(8)
	s_waitcnt lgkmcnt(0)
	s_barrier
	s_setprio 1
	s_waitcnt lgkmcnt(0)
	v_mfma_f32_16x16x32_bf16 v[92:95], v[128:131], v[198:201], v[92:95]
	v_mfma_f32_16x16x32_bf16 v[88:91], v[136:139], v[198:201], v[88:91]
	v_mfma_f32_16x16x32_bf16 v[84:87], v[128:131], v[206:209], v[84:87]
	v_mfma_f32_16x16x32_bf16 v[80:83], v[136:139], v[206:209], v[80:83]
	v_mfma_f32_16x16x32_bf16 v[76:79], v[128:131], v[214:217], v[76:79]
	v_mfma_f32_16x16x32_bf16 v[72:75], v[136:139], v[214:217], v[72:75]
	v_mfma_f32_16x16x32_bf16 v[68:71], v[128:131], v[222:225], v[68:71]
	v_mfma_f32_16x16x32_bf16 v[64:67], v[136:139], v[222:225], v[64:67]
	v_mfma_f32_16x16x32_bf16 v[92:95], v[132:135], v[202:205], v[92:95]
	v_mfma_f32_16x16x32_bf16 v[88:91], v[140:143], v[202:205], v[88:91]
	v_mfma_f32_16x16x32_bf16 v[84:87], v[132:135], v[210:213], v[84:87]
	v_mfma_f32_16x16x32_bf16 v[80:83], v[140:143], v[210:213], v[80:83]
	v_mfma_f32_16x16x32_bf16 v[76:79], v[132:135], v[218:221], v[76:79]
	v_mfma_f32_16x16x32_bf16 v[72:75], v[140:143], v[218:221], v[72:75]
	v_mfma_f32_16x16x32_bf16 v[68:71], v[132:135], v[226:229], v[68:71]
	v_mfma_f32_16x16x32_bf16 v[64:67], v[140:143], v[226:229], v[64:67]
	s_setprio 0
	s_setprio 1
	v_mfma_f32_16x16x32_bf16 v[28:31], v[164:167], v[198:201], v[28:31]
	v_mfma_f32_16x16x32_bf16 v[24:27], v[190:193], v[198:201], v[24:27]
	v_mfma_f32_16x16x32_bf16 v[20:23], v[164:167], v[206:209], v[20:23]
	v_mfma_f32_16x16x32_bf16 v[16:19], v[190:193], v[206:209], v[16:19]
	v_mfma_f32_16x16x32_bf16 v[12:15], v[164:167], v[214:217], v[12:15]
	v_mfma_f32_16x16x32_bf16 v[8:11], v[190:193], v[214:217], v[8:11]
	v_mfma_f32_16x16x32_bf16 v[4:7], v[164:167], v[222:225], v[4:7]
	v_mfma_f32_16x16x32_bf16 v[0:3], v[190:193], v[222:225], v[0:3]
	v_mfma_f32_16x16x32_bf16 v[28:31], v[168:171], v[202:205], v[28:31]
	v_mfma_f32_16x16x32_bf16 v[24:27], v[194:197], v[202:205], v[24:27]
	v_mfma_f32_16x16x32_bf16 v[20:23], v[168:171], v[210:213], v[20:23]
	v_mfma_f32_16x16x32_bf16 v[16:19], v[194:197], v[210:213], v[16:19]
	v_mfma_f32_16x16x32_bf16 v[12:15], v[168:171], v[218:221], v[12:15]
	v_mfma_f32_16x16x32_bf16 v[8:11], v[194:197], v[218:221], v[8:11]
	v_mfma_f32_16x16x32_bf16 v[4:7], v[168:171], v[226:229], v[4:7]
	v_mfma_f32_16x16x32_bf16 v[0:3], v[194:197], v[226:229], v[0:3]
	s_setprio 0
	s_barrier
	s_add_i32 s86, 0, 0x18000
	s_add_i32 s87, 0, 0x1c000
	v_add_u32_e32 v140, s86, v186
	v_add_u32_e32 v144, s87, v186
	ds_read_b128 v[128:131], v140
	ds_read_b128 v[132:135], v140 offset:1024
	ds_read_b128 v[136:139], v140 offset:2048
	ds_read_b128 v[140:143], v140 offset:3072
	ds_read_b128 v[164:167], v144
	ds_read_b128 v[168:171], v144 offset:1024
	ds_read_b128 v[190:193], v144 offset:2048
	ds_read_b128 v[194:197], v144 offset:3072
	s_add_u32 s50, s50, 0x80000
	s_addc_u32 s51, s51, 0
	s_mov_b32 m0, s9
	v_lshl_add_u64 v[238:239], s[50:51], 0, v[158:159]
	ds_read_b128 v[198:201], v188 offset:32768
	ds_read_b128 v[202:205], v188 offset:33792
	ds_read_b128 v[206:209], v188 offset:34816
	ds_read_b128 v[210:213], v188 offset:35840
	ds_read_b128 v[214:217], v188 offset:36864
	ds_read_b128 v[218:221], v188 offset:37888
	ds_read_b128 v[222:225], v188 offset:38912
	ds_read_b128 v[226:229], v188 offset:39936
	global_load_lds_dwordx4 v[238:239], off
	v_lshl_add_u64 v[238:239], s[50:51], 0, v[154:155]
	s_mov_b32 m0, s26
	s_nop 0
	global_load_lds_dwordx4 v[238:239], off
	s_waitcnt vmcnt(8)
	s_waitcnt lgkmcnt(0)
	s_barrier
	s_setprio 1
	s_waitcnt lgkmcnt(0)
	v_mfma_f32_16x16x32_bf16 v[124:127], v[128:131], v[198:201], v[124:127]
	v_mfma_f32_16x16x32_bf16 v[120:123], v[136:139], v[198:201], v[120:123]
	v_mfma_f32_16x16x32_bf16 v[116:119], v[128:131], v[206:209], v[116:119]
	v_mfma_f32_16x16x32_bf16 v[112:115], v[136:139], v[206:209], v[112:115]
	v_mfma_f32_16x16x32_bf16 v[108:111], v[128:131], v[214:217], v[108:111]
	v_mfma_f32_16x16x32_bf16 v[104:107], v[136:139], v[214:217], v[104:107]
	v_mfma_f32_16x16x32_bf16 v[100:103], v[128:131], v[222:225], v[100:103]
	v_mfma_f32_16x16x32_bf16 v[96:99], v[136:139], v[222:225], v[96:99]
	v_mfma_f32_16x16x32_bf16 v[124:127], v[132:135], v[202:205], v[124:127]
	v_mfma_f32_16x16x32_bf16 v[120:123], v[140:143], v[202:205], v[120:123]
	v_mfma_f32_16x16x32_bf16 v[116:119], v[132:135], v[210:213], v[116:119]
	v_mfma_f32_16x16x32_bf16 v[112:115], v[140:143], v[210:213], v[112:115]
	v_mfma_f32_16x16x32_bf16 v[108:111], v[132:135], v[218:221], v[108:111]
	v_mfma_f32_16x16x32_bf16 v[104:107], v[140:143], v[218:221], v[104:107]
	v_mfma_f32_16x16x32_bf16 v[100:103], v[132:135], v[226:229], v[100:103]
	v_mfma_f32_16x16x32_bf16 v[96:99], v[140:143], v[226:229], v[96:99]
	s_setprio 0
	s_setprio 1
	v_mfma_f32_16x16x32_bf16 v[60:63], v[164:167], v[198:201], v[60:63]
	v_mfma_f32_16x16x32_bf16 v[56:59], v[190:193], v[198:201], v[56:59]
	v_mfma_f32_16x16x32_bf16 v[52:55], v[164:167], v[206:209], v[52:55]
	v_mfma_f32_16x16x32_bf16 v[48:51], v[190:193], v[206:209], v[48:51]
	v_mfma_f32_16x16x32_bf16 v[44:47], v[164:167], v[214:217], v[44:47]
	v_mfma_f32_16x16x32_bf16 v[40:43], v[190:193], v[214:217], v[40:43]
	v_mfma_f32_16x16x32_bf16 v[36:39], v[164:167], v[222:225], v[36:39]
	v_mfma_f32_16x16x32_bf16 v[32:35], v[190:193], v[222:225], v[32:35]
	v_mfma_f32_16x16x32_bf16 v[60:63], v[168:171], v[202:205], v[60:63]
	v_mfma_f32_16x16x32_bf16 v[56:59], v[194:197], v[202:205], v[56:59]
	v_mfma_f32_16x16x32_bf16 v[52:55], v[168:171], v[210:213], v[52:55]
	v_mfma_f32_16x16x32_bf16 v[48:51], v[194:197], v[210:213], v[48:51]
	v_mfma_f32_16x16x32_bf16 v[44:47], v[168:171], v[218:221], v[44:47]
	v_mfma_f32_16x16x32_bf16 v[40:43], v[194:197], v[218:221], v[40:43]
	v_mfma_f32_16x16x32_bf16 v[36:39], v[168:171], v[226:229], v[36:39]
	v_mfma_f32_16x16x32_bf16 v[32:35], v[194:197], v[226:229], v[32:35]
	s_setprio 0
	s_barrier
	s_add_i32 s50, s86, s4
	v_lshl_add_u64 v[230:231], v[230:231], 0, s[68:69]
	s_mov_b32 m0, s50
	ds_read_b128 v[198:201], v188 offset:49152
	ds_read_b128 v[202:205], v188 offset:50176
	ds_read_b128 v[206:209], v188 offset:51200
	ds_read_b128 v[210:213], v188 offset:52224
	ds_read_b128 v[214:217], v188 offset:53248
	ds_read_b128 v[218:221], v188 offset:54272
	ds_read_b128 v[222:225], v188 offset:55296
	ds_read_b128 v[226:229], v188 offset:56320
	global_load_lds_dwordx4 v[230:231], off
	s_add_i32 m0, s50, 0x2000
	s_add_u32 s14, s14, 0x80080
	v_lshl_add_u64 v[230:231], v[232:233], 0, s[68:69]
	s_addc_u32 s15, s15, 0
	s_add_i32 s50, s87, s4
	global_load_lds_dwordx4 v[230:231], off
	v_lshl_add_u64 v[230:231], s[14:15], 0, v[156:157]
	s_mov_b32 m0, s50
	s_nop 0
	global_load_lds_dwordx4 v[230:231], off
	v_lshl_add_u64 v[230:231], s[14:15], 0, v[152:153]
	s_add_i32 m0, s50, 0x2000
	s_nop 0
	global_load_lds_dwordx4 v[230:231], off
	v_lshl_add_u64 v[230:231], v[234:235], 0, s[68:69]
	s_mov_b32 m0, s70
	s_nop 0
	global_load_lds_dwordx4 v[230:231], off
	v_lshl_add_u64 v[230:231], v[236:237], 0, s[68:69]
	s_mov_b32 m0, s76
	s_nop 0
	global_load_lds_dwordx4 v[230:231], off
	s_waitcnt vmcnt(8)
	s_waitcnt lgkmcnt(0)
	s_barrier
	s_setprio 1
	s_waitcnt lgkmcnt(0)
	v_mfma_f32_16x16x32_bf16 v[92:95], v[128:131], v[198:201], v[92:95]
	v_mfma_f32_16x16x32_bf16 v[88:91], v[136:139], v[198:201], v[88:91]
	v_mfma_f32_16x16x32_bf16 v[84:87], v[128:131], v[206:209], v[84:87]
	v_mfma_f32_16x16x32_bf16 v[80:83], v[136:139], v[206:209], v[80:83]
	v_mfma_f32_16x16x32_bf16 v[76:79], v[128:131], v[214:217], v[76:79]
	v_mfma_f32_16x16x32_bf16 v[72:75], v[136:139], v[214:217], v[72:75]
	v_mfma_f32_16x16x32_bf16 v[68:71], v[128:131], v[222:225], v[68:71]
	v_mfma_f32_16x16x32_bf16 v[64:67], v[136:139], v[222:225], v[64:67]
	v_mfma_f32_16x16x32_bf16 v[92:95], v[132:135], v[202:205], v[92:95]
	v_mfma_f32_16x16x32_bf16 v[88:91], v[140:143], v[202:205], v[88:91]
	v_mfma_f32_16x16x32_bf16 v[84:87], v[132:135], v[210:213], v[84:87]
	v_mfma_f32_16x16x32_bf16 v[80:83], v[140:143], v[210:213], v[80:83]
	v_mfma_f32_16x16x32_bf16 v[76:79], v[132:135], v[218:221], v[76:79]
	v_mfma_f32_16x16x32_bf16 v[72:75], v[140:143], v[218:221], v[72:75]
	v_mfma_f32_16x16x32_bf16 v[68:71], v[132:135], v[226:229], v[68:71]
	v_mfma_f32_16x16x32_bf16 v[64:67], v[140:143], v[226:229], v[64:67]
	s_setprio 0
	s_setprio 1
	v_mfma_f32_16x16x32_bf16 v[28:31], v[164:167], v[198:201], v[28:31]
	v_mfma_f32_16x16x32_bf16 v[24:27], v[190:193], v[198:201], v[24:27]
	v_mfma_f32_16x16x32_bf16 v[20:23], v[164:167], v[206:209], v[20:23]
	v_mfma_f32_16x16x32_bf16 v[16:19], v[190:193], v[206:209], v[16:19]
	v_mfma_f32_16x16x32_bf16 v[12:15], v[164:167], v[214:217], v[12:15]
	v_mfma_f32_16x16x32_bf16 v[8:11], v[190:193], v[214:217], v[8:11]
	v_mfma_f32_16x16x32_bf16 v[4:7], v[164:167], v[222:225], v[4:7]
	v_mfma_f32_16x16x32_bf16 v[0:3], v[190:193], v[222:225], v[0:3]
	v_mfma_f32_16x16x32_bf16 v[28:31], v[168:171], v[202:205], v[28:31]
	v_mfma_f32_16x16x32_bf16 v[24:27], v[194:197], v[202:205], v[24:27]
	v_mfma_f32_16x16x32_bf16 v[20:23], v[168:171], v[210:213], v[20:23]
	v_mfma_f32_16x16x32_bf16 v[16:19], v[194:197], v[210:213], v[16:19]
	v_mfma_f32_16x16x32_bf16 v[12:15], v[168:171], v[218:221], v[12:15]
	v_mfma_f32_16x16x32_bf16 v[8:11], v[194:197], v[218:221], v[8:11]
	v_mfma_f32_16x16x32_bf16 v[4:7], v[168:171], v[226:229], v[4:7]
	v_mfma_f32_16x16x32_bf16 v[0:3], v[194:197], v[226:229], v[0:3]
	s_setprio 0
	s_barrier
	s_add_i32 s14, s85, 2
	s_add_u32 s12, s12, 0x100
	s_addc_u32 s13, s13, 0
	s_add_u32 s83, s83, 0x100
	s_addc_u32 s84, s84, 0
	s_cmp_ge_u32 s85, s1
	s_mov_b32 s85, s14
	s_cbranch_scc0 .LBB0_785
	s_and_b64 vcc, exec, s[28:29]
	s_cbranch_vccz .LBB0_788
	s_barrier

.LBB0_991:
	s_add_u32 s28, s24, 0xfff80080
	s_addc_u32 s29, s25, -1
	s_add_i32 s60, 0, 0x10000
	s_cmp_eq_u32 s58, 28
	s_cselect_b32 s31, s19, s29
	s_cselect_b32 s30, s39, s28
	v_add_u32_e32 v138, s60, v141
	s_cselect_b32 s29, s17, s57
	s_cselect_b32 s28, s55, s56
	s_add_i32 s62, 0, 0x14000
	ds_read_b128 v[152:155], v138
	ds_read_b128 v[156:159], v138 offset:1024
	ds_read_b128 v[160:163], v138 offset:2048
	ds_read_b128 v[164:167], v138 offset:3072
	v_add_u32_e32 v138, s62, v141
	ds_read_b128 v[168:171], v138
	ds_read_b128 v[186:189], v138 offset:1024
	ds_read_b128 v[190:193], v138 offset:2048
	ds_read_b128 v[194:197], v138 offset:3072
	v_lshl_add_u64 v[138:139], s[24:25], 0, v[134:135]
	s_add_i32 m0, s46, 0xc000
	ds_read_b128 v[198:201], v143
	ds_read_b128 v[202:205], v143 offset:1024
	ds_read_b128 v[206:209], v143 offset:2048
	ds_read_b128 v[210:213], v143 offset:3072
	ds_read_b128 v[214:217], v143 offset:4096
	ds_read_b128 v[218:221], v143 offset:5120
	ds_read_b128 v[222:225], v143 offset:6144
	ds_read_b128 v[226:229], v143 offset:7168
	global_load_lds_dwordx4 v[138:139], off
	v_lshl_add_u64 v[138:139], s[24:25], 0, v[136:137]
	s_add_i32 m0, s46, 0xe000
	s_nop 0
	global_load_lds_dwordx4 v[138:139], off
	s_waitcnt vmcnt(8)
	s_waitcnt lgkmcnt(0)
	s_barrier
	s_setprio 1
	s_waitcnt lgkmcnt(0)
	v_mfma_f32_16x16x32_bf16 v[124:127], v[152:155], v[198:201], v[124:127]
	v_mfma_f32_16x16x32_bf16 v[120:123], v[160:163], v[198:201], v[120:123]
	v_mfma_f32_16x16x32_bf16 v[108:111], v[152:155], v[206:209], v[108:111]
	v_mfma_f32_16x16x32_bf16 v[104:107], v[160:163], v[206:209], v[104:107]
	v_mfma_f32_16x16x32_bf16 v[92:95], v[152:155], v[214:217], v[92:95]
	v_mfma_f32_16x16x32_bf16 v[88:91], v[160:163], v[214:217], v[88:91]
	v_mfma_f32_16x16x32_bf16 v[76:79], v[152:155], v[222:225], v[76:79]
	v_mfma_f32_16x16x32_bf16 v[72:75], v[160:163], v[222:225], v[72:75]
	v_mfma_f32_16x16x32_bf16 v[124:127], v[156:159], v[202:205], v[124:127]
	v_mfma_f32_16x16x32_bf16 v[120:123], v[164:167], v[202:205], v[120:123]
	v_mfma_f32_16x16x32_bf16 v[108:111], v[156:159], v[210:213], v[108:111]
	v_mfma_f32_16x16x32_bf16 v[104:107], v[164:167], v[210:213], v[104:107]
	v_mfma_f32_16x16x32_bf16 v[92:95], v[156:159], v[218:221], v[92:95]
	v_mfma_f32_16x16x32_bf16 v[88:91], v[164:167], v[218:221], v[88:91]
	v_mfma_f32_16x16x32_bf16 v[76:79], v[156:159], v[226:229], v[76:79]
	v_mfma_f32_16x16x32_bf16 v[72:75], v[164:167], v[226:229], v[72:75]
	s_setprio 0
	s_setprio 1
	v_mfma_f32_16x16x32_bf16 v[116:119], v[168:171], v[198:201], v[116:119]
	v_mfma_f32_16x16x32_bf16 v[112:115], v[190:193], v[198:201], v[112:115]
	v_mfma_f32_16x16x32_bf16 v[100:103], v[168:171], v[206:209], v[100:103]
	v_mfma_f32_16x16x32_bf16 v[96:99], v[190:193], v[206:209], v[96:99]
	v_mfma_f32_16x16x32_bf16 v[84:87], v[168:171], v[214:217], v[84:87]
	v_mfma_f32_16x16x32_bf16 v[80:83], v[190:193], v[214:217], v[80:83]
	v_mfma_f32_16x16x32_bf16 v[68:71], v[168:171], v[222:225], v[68:71]
	v_mfma_f32_16x16x32_bf16 v[64:67], v[190:193], v[222:225], v[64:67]
	v_mfma_f32_16x16x32_bf16 v[116:119], v[186:189], v[202:205], v[116:119]
	v_mfma_f32_16x16x32_bf16 v[112:115], v[194:197], v[202:205], v[112:115]
	v_mfma_f32_16x16x32_bf16 v[100:103], v[186:189], v[210:213], v[100:103]
	v_mfma_f32_16x16x32_bf16 v[96:99], v[194:197], v[210:213], v[96:99]
	v_mfma_f32_16x16x32_bf16 v[84:87], v[186:189], v[218:221], v[84:87]
	v_mfma_f32_16x16x32_bf16 v[80:83], v[194:197], v[218:221], v[80:83]
	v_mfma_f32_16x16x32_bf16 v[68:71], v[186:189], v[226:229], v[68:71]
	v_mfma_f32_16x16x32_bf16 v[64:67], v[194:197], v[226:229], v[64:67]
	s_setprio 0
	s_barrier
	s_add_i32 s60, s60, s35
	v_lshl_add_u64 v[138:139], s[28:29], 0, v[144:145]
	s_mov_b32 m0, s60
	ds_read_b128 v[198:201], v143 offset:16384
	ds_read_b128 v[202:205], v143 offset:17408
	ds_read_b128 v[206:209], v143 offset:18432
	ds_read_b128 v[210:213], v143 offset:19456
	ds_read_b128 v[214:217], v143 offset:20480
	ds_read_b128 v[218:221], v143 offset:21504
	ds_read_b128 v[222:225], v143 offset:22528
	ds_read_b128 v[226:229], v143 offset:23552
	global_load_lds_dwordx4 v[138:139], off
	s_add_i32 m0, s60, 0x2000
	s_add_u32 s60, s28, 0x80000
	v_lshl_add_u64 v[230:231], s[28:29], 0, v[128:129]
	s_addc_u32 s61, s29, 0
	s_add_i32 s62, s62, s35
	global_load_lds_dwordx4 v[230:231], off
	v_lshl_add_u64 v[232:233], s[60:61], 0, v[144:145]
	s_mov_b32 m0, s62
	v_lshl_add_u64 v[234:235], s[30:31], 0, v[130:131]
	global_load_lds_dwordx4 v[232:233], off
	v_lshl_add_u64 v[232:233], s[60:61], 0, v[128:129]
	s_add_i32 m0, s62, 0x2000
	s_nop 0
	global_load_lds_dwordx4 v[232:233], off
	v_lshl_add_u64 v[232:233], s[30:31], 0, v[132:133]
	s_mov_b32 m0, s46
	s_nop 0
	global_load_lds_dwordx4 v[232:233], off
	s_mov_b32 m0, s47
	s_nop 0
	global_load_lds_dwordx4 v[234:235], off
	s_waitcnt vmcnt(8)
	s_waitcnt lgkmcnt(0)
	s_barrier
	s_setprio 1
	s_waitcnt lgkmcnt(0)
	v_mfma_f32_16x16x32_bf16 v[60:63], v[152:155], v[198:201], v[60:63]
	v_mfma_f32_16x16x32_bf16 v[56:59], v[160:163], v[198:201], v[56:59]
	v_mfma_f32_16x16x32_bf16 v[44:47], v[152:155], v[206:209], v[44:47]
	v_mfma_f32_16x16x32_bf16 v[40:43], v[160:163], v[206:209], v[40:43]
	v_mfma_f32_16x16x32_bf16 v[28:31], v[152:155], v[214:217], v[28:31]
	v_mfma_f32_16x16x32_bf16 v[24:27], v[160:163], v[214:217], v[24:27]
	v_mfma_f32_16x16x32_bf16 v[12:15], v[152:155], v[222:225], v[12:15]
	v_mfma_f32_16x16x32_bf16 v[8:11], v[160:163], v[222:225], v[8:11]
	v_mfma_f32_16x16x32_bf16 v[60:63], v[156:159], v[202:205], v[60:63]
	v_mfma_f32_16x16x32_bf16 v[56:59], v[164:167], v[202:205], v[56:59]
	v_mfma_f32_16x16x32_bf16 v[44:47], v[156:159], v[210:213], v[44:47]
	v_mfma_f32_16x16x32_bf16 v[40:43], v[164:167], v[210:213], v[40:43]
	v_mfma_f32_16x16x32_bf16 v[28:31], v[156:159], v[218:221], v[28:31]
	v_mfma_f32_16x16x32_bf16 v[24:27], v[164:167], v[218:221], v[24:27]
	v_mfma_f32_16x16x32_bf16 v[12:15], v[156:159], v[226:229], v[12:15]
	v_mfma_f32_16x16x32_bf16 v[8:11], v[164:167], v[226:229], v[8:11]
	s_setprio 0
	s_setprio 1
	v_mfma_f32_16x16x32_bf16 v[52:55], v[168:171], v[198:201], v[52:55]
	v_mfma_f32_16x16x32_bf16 v[48:51], v[190:193], v[198:201], v[48:51]
	v_mfma_f32_16x16x32_bf16 v[36:39], v[168:171], v[206:209], v[36:39]
	v_mfma_f32_16x16x32_bf16 v[32:35], v[190:193], v[206:209], v[32:35]
	v_mfma_f32_16x16x32_bf16 v[20:23], v[168:171], v[214:217], v[20:23]
	v_mfma_f32_16x16x32_bf16 v[16:19], v[190:193], v[214:217], v[16:19]
	v_mfma_f32_16x16x32_bf16 v[4:7], v[168:171], v[222:225], v[4:7]
	v_mfma_f32_16x16x32_bf16 v[0:3], v[190:193], v[222:225], v[0:3]
	v_mfma_f32_16x16x32_bf16 v[52:55], v[186:189], v[202:205], v[52:55]
	v_mfma_f32_16x16x32_bf16 v[48:51], v[194:197], v[202:205], v[48:51]
	v_mfma_f32_16x16x32_bf16 v[36:39], v[186:189], v[210:213], v[36:39]
	v_mfma_f32_16x16x32_bf16 v[32:35], v[194:197], v[210:213], v[32:35]
	v_mfma_f32_16x16x32_bf16 v[20:23], v[186:189], v[218:221], v[20:23]
	v_mfma_f32_16x16x32_bf16 v[16:19], v[194:197], v[218:221], v[16:19]
	v_mfma_f32_16x16x32_bf16 v[4:7], v[186:189], v[226:229], v[4:7]
	v_mfma_f32_16x16x32_bf16 v[0:3], v[194:197], v[226:229], v[0:3]
	s_setprio 0
	s_barrier
	s_add_i32 s60, 0, 0x18000
	s_add_i32 s61, 0, 0x1c000
	v_add_u32_e32 v164, s60, v141
	v_add_u32_e32 v185, s61, v141
	ds_read_b128 v[152:155], v164
	ds_read_b128 v[156:159], v164 offset:1024
	ds_read_b128 v[160:163], v164 offset:2048
	ds_read_b128 v[164:167], v164 offset:3072
	ds_read_b128 v[168:171], v185
	ds_read_b128 v[186:189], v185 offset:1024
	ds_read_b128 v[190:193], v185 offset:2048
	ds_read_b128 v[194:197], v185 offset:3072
	s_add_u32 s30, s30, 0x80000
	s_addc_u32 s31, s31, 0
	s_mov_b32 m0, s48
	v_lshl_add_u64 v[236:237], s[30:31], 0, v[132:133]
	ds_read_b128 v[198:201], v143 offset:32768
	ds_read_b128 v[202:205], v143 offset:33792
	ds_read_b128 v[206:209], v143 offset:34816
	ds_read_b128 v[210:213], v143 offset:35840
	ds_read_b128 v[214:217], v143 offset:36864
	ds_read_b128 v[218:221], v143 offset:37888
	ds_read_b128 v[222:225], v143 offset:38912
	ds_read_b128 v[226:229], v143 offset:39936
	global_load_lds_dwordx4 v[236:237], off
	v_lshl_add_u64 v[236:237], s[30:31], 0, v[130:131]
	s_mov_b32 m0, s49
	s_nop 0
	global_load_lds_dwordx4 v[236:237], off
	s_waitcnt vmcnt(8)
	s_waitcnt lgkmcnt(0)
	s_barrier
	s_setprio 1
	s_waitcnt lgkmcnt(0)
	v_mfma_f32_16x16x32_bf16 v[124:127], v[152:155], v[198:201], v[124:127]
	v_mfma_f32_16x16x32_bf16 v[120:123], v[160:163], v[198:201], v[120:123]
	v_mfma_f32_16x16x32_bf16 v[108:111], v[152:155], v[206:209], v[108:111]
	v_mfma_f32_16x16x32_bf16 v[104:107], v[160:163], v[206:209], v[104:107]
	v_mfma_f32_16x16x32_bf16 v[92:95], v[152:155], v[214:217], v[92:95]
	v_mfma_f32_16x16x32_bf16 v[88:91], v[160:163], v[214:217], v[88:91]
	v_mfma_f32_16x16x32_bf16 v[76:79], v[152:155], v[222:225], v[76:79]
	v_mfma_f32_16x16x32_bf16 v[72:75], v[160:163], v[222:225], v[72:75]
	v_mfma_f32_16x16x32_bf16 v[124:127], v[156:159], v[202:205], v[124:127]
	v_mfma_f32_16x16x32_bf16 v[120:123], v[164:167], v[202:205], v[120:123]
	v_mfma_f32_16x16x32_bf16 v[108:111], v[156:159], v[210:213], v[108:111]
	v_mfma_f32_16x16x32_bf16 v[104:107], v[164:167], v[210:213], v[104:107]
	v_mfma_f32_16x16x32_bf16 v[92:95], v[156:159], v[218:221], v[92:95]
	v_mfma_f32_16x16x32_bf16 v[88:91], v[164:167], v[218:221], v[88:91]
	v_mfma_f32_16x16x32_bf16 v[76:79], v[156:159], v[226:229], v[76:79]
	v_mfma_f32_16x16x32_bf16 v[72:75], v[164:167], v[226:229], v[72:75]
	s_setprio 0
	s_setprio 1
	v_mfma_f32_16x16x32_bf16 v[116:119], v[168:171], v[198:201], v[116:119]
	v_mfma_f32_16x16x32_bf16 v[112:115], v[190:193], v[198:201], v[112:115]
	v_mfma_f32_16x16x32_bf16 v[100:103], v[168:171], v[206:209], v[100:103]
	v_mfma_f32_16x16x32_bf16 v[96:99], v[190:193], v[206:209], v[96:99]
	v_mfma_f32_16x16x32_bf16 v[84:87], v[168:171], v[214:217], v[84:87]
	v_mfma_f32_16x16x32_bf16 v[80:83], v[190:193], v[214:217], v[80:83]
	v_mfma_f32_16x16x32_bf16 v[68:71], v[168:171], v[222:225], v[68:71]
	v_mfma_f32_16x16x32_bf16 v[64:67], v[190:193], v[222:225], v[64:67]
	v_mfma_f32_16x16x32_bf16 v[116:119], v[186:189], v[202:205], v[116:119]
	v_mfma_f32_16x16x32_bf16 v[112:115], v[194:197], v[202:205], v[112:115]
	v_mfma_f32_16x16x32_bf16 v[100:103], v[186:189], v[210:213], v[100:103]
	v_mfma_f32_16x16x32_bf16 v[96:99], v[194:197], v[210:213], v[96:99]
	v_mfma_f32_16x16x32_bf16 v[84:87], v[186:189], v[218:221], v[84:87]
	v_mfma_f32_16x16x32_bf16 v[80:83], v[194:197], v[218:221], v[80:83]
	v_mfma_f32_16x16x32_bf16 v[68:71], v[186:189], v[226:229], v[68:71]
	v_mfma_f32_16x16x32_bf16 v[64:67], v[194:197], v[226:229], v[64:67]
	s_setprio 0
	s_barrier
	s_add_i32 s30, s60, s35
	v_lshl_add_u64 v[138:139], v[138:139], 0, s[68:69]
	s_mov_b32 m0, s30
	ds_read_b128 v[198:201], v143 offset:49152
	ds_read_b128 v[202:205], v143 offset:50176
	ds_read_b128 v[206:209], v143 offset:51200
	ds_read_b128 v[210:213], v143 offset:52224
	ds_read_b128 v[214:217], v143 offset:53248
	ds_read_b128 v[218:221], v143 offset:54272
	ds_read_b128 v[222:225], v143 offset:55296
	ds_read_b128 v[226:229], v143 offset:56320
	global_load_lds_dwordx4 v[138:139], off
	s_add_i32 m0, s30, 0x2000
	s_add_u32 s28, s28, 0x80080
	v_lshl_add_u64 v[138:139], v[230:231], 0, s[68:69]
	s_addc_u32 s29, s29, 0
	s_add_i32 s30, s61, s35
	global_load_lds_dwordx4 v[138:139], off
	v_lshl_add_u64 v[138:139], s[28:29], 0, v[144:145]
	s_mov_b32 m0, s30
	s_nop 0
	global_load_lds_dwordx4 v[138:139], off
	v_lshl_add_u64 v[138:139], s[28:29], 0, v[128:129]
	s_add_i32 m0, s30, 0x2000
	s_nop 0
	global_load_lds_dwordx4 v[138:139], off
	v_lshl_add_u64 v[138:139], v[232:233], 0, s[68:69]
	s_mov_b32 m0, s50
	s_nop 0
	global_load_lds_dwordx4 v[138:139], off
	v_lshl_add_u64 v[138:139], v[234:235], 0, s[68:69]
	s_mov_b32 m0, s51
	s_nop 0
	global_load_lds_dwordx4 v[138:139], off
	s_waitcnt vmcnt(8)
	s_waitcnt lgkmcnt(0)
	s_barrier
	s_setprio 1
	s_waitcnt lgkmcnt(0)
	v_mfma_f32_16x16x32_bf16 v[60:63], v[152:155], v[198:201], v[60:63]
	v_mfma_f32_16x16x32_bf16 v[56:59], v[160:163], v[198:201], v[56:59]
	v_mfma_f32_16x16x32_bf16 v[44:47], v[152:155], v[206:209], v[44:47]
	v_mfma_f32_16x16x32_bf16 v[40:43], v[160:163], v[206:209], v[40:43]
	v_mfma_f32_16x16x32_bf16 v[28:31], v[152:155], v[214:217], v[28:31]
	v_mfma_f32_16x16x32_bf16 v[24:27], v[160:163], v[214:217], v[24:27]
	v_mfma_f32_16x16x32_bf16 v[12:15], v[152:155], v[222:225], v[12:15]
	v_mfma_f32_16x16x32_bf16 v[8:11], v[160:163], v[222:225], v[8:11]
	v_mfma_f32_16x16x32_bf16 v[60:63], v[156:159], v[202:205], v[60:63]
	v_mfma_f32_16x16x32_bf16 v[56:59], v[164:167], v[202:205], v[56:59]
	v_mfma_f32_16x16x32_bf16 v[44:47], v[156:159], v[210:213], v[44:47]
	v_mfma_f32_16x16x32_bf16 v[40:43], v[164:167], v[210:213], v[40:43]
	v_mfma_f32_16x16x32_bf16 v[28:31], v[156:159], v[218:221], v[28:31]
	v_mfma_f32_16x16x32_bf16 v[24:27], v[164:167], v[218:221], v[24:27]
	v_mfma_f32_16x16x32_bf16 v[12:15], v[156:159], v[226:229], v[12:15]
	v_mfma_f32_16x16x32_bf16 v[8:11], v[164:167], v[226:229], v[8:11]
	s_setprio 0
	s_setprio 1
	v_mfma_f32_16x16x32_bf16 v[52:55], v[168:171], v[198:201], v[52:55]
	v_mfma_f32_16x16x32_bf16 v[48:51], v[190:193], v[198:201], v[48:51]
	v_mfma_f32_16x16x32_bf16 v[36:39], v[168:171], v[206:209], v[36:39]
	v_mfma_f32_16x16x32_bf16 v[32:35], v[190:193], v[206:209], v[32:35]
	v_mfma_f32_16x16x32_bf16 v[20:23], v[168:171], v[214:217], v[20:23]
	v_mfma_f32_16x16x32_bf16 v[16:19], v[190:193], v[214:217], v[16:19]
	v_mfma_f32_16x16x32_bf16 v[4:7], v[168:171], v[222:225], v[4:7]
	v_mfma_f32_16x16x32_bf16 v[0:3], v[190:193], v[222:225], v[0:3]
	v_mfma_f32_16x16x32_bf16 v[52:55], v[186:189], v[202:205], v[52:55]
	v_mfma_f32_16x16x32_bf16 v[48:51], v[194:197], v[202:205], v[48:51]
	v_mfma_f32_16x16x32_bf16 v[36:39], v[186:189], v[210:213], v[36:39]
	v_mfma_f32_16x16x32_bf16 v[32:35], v[194:197], v[210:213], v[32:35]
	v_mfma_f32_16x16x32_bf16 v[20:23], v[186:189], v[218:221], v[20:23]
	v_mfma_f32_16x16x32_bf16 v[16:19], v[194:197], v[218:221], v[16:19]
	v_mfma_f32_16x16x32_bf16 v[4:7], v[186:189], v[226:229], v[4:7]
	v_mfma_f32_16x16x32_bf16 v[0:3], v[194:197], v[226:229], v[0:3]
	s_setprio 0
	s_barrier
	s_add_i32 s58, s58, 2
	s_add_u32 s24, s24, 0x100
	s_addc_u32 s25, s25, 0
	s_add_u32 s56, s56, 0x100
	s_addc_u32 s57, s57, 0
	s_cmp_gt_u32 s58, 29
	s_cbranch_scc0 .LBB0_991
	s_and_b64 vcc, exec, s[14:15]
	s_cbranch_vccz .LBB0_994
	s_barrier

.LBB0_1057:
	s_add_u32 s22, s20, 0xffe00080
	s_addc_u32 s23, s21, -1
	s_add_i32 s62, 0, 0x10000
	s_cmp_eq_u32 s39, s61
	s_cselect_b32 s25, s17, s23
	s_cselect_b32 s24, s55, s22
	v_add_u32_e32 v144, s62, v163
	s_cselect_b32 s23, s56, s60
	s_cselect_b32 s22, s57, s58
	s_add_i32 s67, 0, 0x14000
	ds_read_b128 v[104:107], v144
	ds_read_b128 v[108:111], v144 offset:1024
	ds_read_b128 v[156:159], v144 offset:2048
	ds_read_b128 v[166:169], v144 offset:3072
	v_add_u32_e32 v144, s67, v163
	ds_read_b128 v[186:189], v144
	ds_read_b128 v[190:193], v144 offset:1024
	ds_read_b128 v[194:197], v144 offset:2048
	ds_read_b128 v[198:201], v144 offset:3072
	v_lshl_add_u64 v[160:161], s[20:21], 0, v[152:153]
	s_add_i32 m0, s5, 0xc000
	ds_read_b128 v[202:205], v165
	ds_read_b128 v[206:209], v165 offset:1024
	ds_read_b128 v[210:213], v165 offset:2048
	ds_read_b128 v[214:217], v165 offset:3072
	ds_read_b128 v[218:221], v165 offset:4096
	ds_read_b128 v[222:225], v165 offset:5120
	ds_read_b128 v[226:229], v165 offset:6144
	ds_read_b128 v[230:233], v165 offset:7168
	global_load_lds_dwordx4 v[160:161], off
	v_lshl_add_u64 v[160:161], s[20:21], 0, v[154:155]
	s_add_i32 m0, s5, 0xe000
	s_nop 0
	global_load_lds_dwordx4 v[160:161], off
	s_waitcnt vmcnt(8)
	s_waitcnt lgkmcnt(0)
	s_barrier
	s_setprio 1
	s_waitcnt lgkmcnt(0)
	v_mfma_f32_16x16x32_bf16 v[132:135], v[104:107], v[202:205], v[132:135]
	v_mfma_f32_16x16x32_bf16 v[128:131], v[156:159], v[202:205], v[128:131]
	v_mfma_f32_16x16x32_bf16 v[124:127], v[104:107], v[210:213], v[124:127]
	v_mfma_f32_16x16x32_bf16 v[120:123], v[156:159], v[210:213], v[120:123]
	v_mfma_f32_16x16x32_bf16 v[116:119], v[104:107], v[218:221], v[116:119]
	v_mfma_f32_16x16x32_bf16 v[112:115], v[156:159], v[218:221], v[112:115]
	v_mfma_f32_16x16x32_bf16 v[100:103], v[104:107], v[226:229], v[100:103]
	v_mfma_f32_16x16x32_bf16 v[96:99], v[156:159], v[226:229], v[96:99]
	v_mfma_f32_16x16x32_bf16 v[132:135], v[108:111], v[206:209], v[132:135]
	v_mfma_f32_16x16x32_bf16 v[128:131], v[166:169], v[206:209], v[128:131]
	v_mfma_f32_16x16x32_bf16 v[124:127], v[108:111], v[214:217], v[124:127]
	v_mfma_f32_16x16x32_bf16 v[120:123], v[166:169], v[214:217], v[120:123]
	v_mfma_f32_16x16x32_bf16 v[116:119], v[108:111], v[222:225], v[116:119]
	v_mfma_f32_16x16x32_bf16 v[112:115], v[166:169], v[222:225], v[112:115]
	v_mfma_f32_16x16x32_bf16 v[100:103], v[108:111], v[230:233], v[100:103]
	v_mfma_f32_16x16x32_bf16 v[96:99], v[166:169], v[230:233], v[96:99]
	s_setprio 0
	s_setprio 1
	v_mfma_f32_16x16x32_bf16 v[60:63], v[186:189], v[202:205], v[60:63]
	v_mfma_f32_16x16x32_bf16 v[56:59], v[194:197], v[202:205], v[56:59]
	v_mfma_f32_16x16x32_bf16 v[52:55], v[186:189], v[210:213], v[52:55]
	v_mfma_f32_16x16x32_bf16 v[48:51], v[194:197], v[210:213], v[48:51]
	v_mfma_f32_16x16x32_bf16 v[44:47], v[186:189], v[218:221], v[44:47]
	v_mfma_f32_16x16x32_bf16 v[40:43], v[194:197], v[218:221], v[40:43]
	v_mfma_f32_16x16x32_bf16 v[36:39], v[186:189], v[226:229], v[36:39]
	v_mfma_f32_16x16x32_bf16 v[32:35], v[194:197], v[226:229], v[32:35]
	v_mfma_f32_16x16x32_bf16 v[60:63], v[190:193], v[206:209], v[60:63]
	v_mfma_f32_16x16x32_bf16 v[56:59], v[198:201], v[206:209], v[56:59]
	v_mfma_f32_16x16x32_bf16 v[52:55], v[190:193], v[214:217], v[52:55]
	v_mfma_f32_16x16x32_bf16 v[48:51], v[198:201], v[214:217], v[48:51]
	v_mfma_f32_16x16x32_bf16 v[44:47], v[190:193], v[222:225], v[44:47]
	v_mfma_f32_16x16x32_bf16 v[40:43], v[198:201], v[222:225], v[40:43]
	v_mfma_f32_16x16x32_bf16 v[36:39], v[190:193], v[230:233], v[36:39]
	v_mfma_f32_16x16x32_bf16 v[32:35], v[198:201], v[230:233], v[32:35]
	s_setprio 0
	s_barrier
	s_add_i32 s62, s62, s4
	v_lshl_add_u64 v[160:161], s[22:23], 0, v[140:141]
	s_mov_b32 m0, s62
	ds_read_b128 v[202:205], v165 offset:16384
	ds_read_b128 v[206:209], v165 offset:17408
	ds_read_b128 v[210:213], v165 offset:18432
	ds_read_b128 v[214:217], v165 offset:19456
	ds_read_b128 v[218:221], v165 offset:20480
	ds_read_b128 v[222:225], v165 offset:21504
	ds_read_b128 v[226:229], v165 offset:22528
	ds_read_b128 v[230:233], v165 offset:23552
	global_load_lds_dwordx4 v[160:161], off
	s_add_i32 m0, s62, 0x2000
	s_add_u32 s62, s22, 0x200000
	v_lshl_add_u64 v[170:171], s[22:23], 0, v[136:137]
	s_addc_u32 s63, s23, 0
	s_add_i32 s67, s67, s4
	global_load_lds_dwordx4 v[170:171], off
	v_lshl_add_u64 v[234:235], s[62:63], 0, v[140:141]
	s_mov_b32 m0, s67
	v_lshl_add_u64 v[236:237], s[24:25], 0, v[138:139]
	global_load_lds_dwordx4 v[234:235], off
	v_lshl_add_u64 v[234:235], s[62:63], 0, v[136:137]
	s_add_i32 m0, s67, 0x2000
	s_nop 0
	global_load_lds_dwordx4 v[234:235], off
	v_lshl_add_u64 v[234:235], s[24:25], 0, v[142:143]
	s_mov_b32 m0, s5
	s_nop 0
	global_load_lds_dwordx4 v[234:235], off
	s_mov_b32 m0, s26
	s_nop 0
	global_load_lds_dwordx4 v[236:237], off
	s_waitcnt vmcnt(8)
	s_waitcnt lgkmcnt(0)
	s_barrier
	s_setprio 1
	s_waitcnt lgkmcnt(0)
	v_mfma_f32_16x16x32_bf16 v[92:95], v[104:107], v[202:205], v[92:95]
	v_mfma_f32_16x16x32_bf16 v[88:91], v[156:159], v[202:205], v[88:91]
	v_mfma_f32_16x16x32_bf16 v[84:87], v[104:107], v[210:213], v[84:87]
	v_mfma_f32_16x16x32_bf16 v[80:83], v[156:159], v[210:213], v[80:83]
	v_mfma_f32_16x16x32_bf16 v[76:79], v[104:107], v[218:221], v[76:79]
	v_mfma_f32_16x16x32_bf16 v[72:75], v[156:159], v[218:221], v[72:75]
	v_mfma_f32_16x16x32_bf16 v[68:71], v[104:107], v[226:229], v[68:71]
	v_mfma_f32_16x16x32_bf16 v[64:67], v[156:159], v[226:229], v[64:67]
	v_mfma_f32_16x16x32_bf16 v[92:95], v[108:111], v[206:209], v[92:95]
	v_mfma_f32_16x16x32_bf16 v[88:91], v[166:169], v[206:209], v[88:91]
	v_mfma_f32_16x16x32_bf16 v[84:87], v[108:111], v[214:217], v[84:87]
	v_mfma_f32_16x16x32_bf16 v[80:83], v[166:169], v[214:217], v[80:83]
	v_mfma_f32_16x16x32_bf16 v[76:79], v[108:111], v[222:225], v[76:79]
	v_mfma_f32_16x16x32_bf16 v[72:75], v[166:169], v[222:225], v[72:75]
	v_mfma_f32_16x16x32_bf16 v[68:71], v[108:111], v[230:233], v[68:71]
	v_mfma_f32_16x16x32_bf16 v[64:67], v[166:169], v[230:233], v[64:67]
	s_setprio 0
	s_setprio 1
	v_mfma_f32_16x16x32_bf16 v[28:31], v[186:189], v[202:205], v[28:31]
	v_mfma_f32_16x16x32_bf16 v[24:27], v[194:197], v[202:205], v[24:27]
	v_mfma_f32_16x16x32_bf16 v[20:23], v[186:189], v[210:213], v[20:23]
	v_mfma_f32_16x16x32_bf16 v[16:19], v[194:197], v[210:213], v[16:19]
	v_mfma_f32_16x16x32_bf16 v[12:15], v[186:189], v[218:221], v[12:15]
	v_mfma_f32_16x16x32_bf16 v[8:11], v[194:197], v[218:221], v[8:11]
	v_mfma_f32_16x16x32_bf16 v[4:7], v[186:189], v[226:229], v[4:7]
	v_mfma_f32_16x16x32_bf16 v[0:3], v[194:197], v[226:229], v[0:3]
	v_mfma_f32_16x16x32_bf16 v[28:31], v[190:193], v[206:209], v[28:31]
	v_mfma_f32_16x16x32_bf16 v[24:27], v[198:201], v[206:209], v[24:27]
	v_mfma_f32_16x16x32_bf16 v[20:23], v[190:193], v[214:217], v[20:23]
	v_mfma_f32_16x16x32_bf16 v[16:19], v[198:201], v[214:217], v[16:19]
	v_mfma_f32_16x16x32_bf16 v[12:15], v[190:193], v[222:225], v[12:15]
	v_mfma_f32_16x16x32_bf16 v[8:11], v[198:201], v[222:225], v[8:11]
	v_mfma_f32_16x16x32_bf16 v[4:7], v[190:193], v[230:233], v[4:7]
	v_mfma_f32_16x16x32_bf16 v[0:3], v[198:201], v[230:233], v[0:3]
	s_setprio 0
	s_barrier
	s_add_i32 s62, 0, 0x18000
	v_add_u32_e32 v144, s62, v163
	s_add_i32 s63, 0, 0x1c000
	ds_read_b128 v[104:107], v144
	ds_read_b128 v[108:111], v144 offset:1024
	ds_read_b128 v[156:159], v144 offset:2048
	ds_read_b128 v[166:169], v144 offset:3072
	v_add_u32_e32 v144, s63, v163
	ds_read_b128 v[186:189], v144
	ds_read_b128 v[190:193], v144 offset:1024
	ds_read_b128 v[194:197], v144 offset:2048
	ds_read_b128 v[198:201], v144 offset:3072
	s_add_u32 s24, s24, 0x200000
	s_addc_u32 s25, s25, 0
	s_mov_b32 m0, s27
	v_lshl_add_u64 v[238:239], s[24:25], 0, v[142:143]
	ds_read_b128 v[202:205], v165 offset:32768
	ds_read_b128 v[206:209], v165 offset:33792
	ds_read_b128 v[210:213], v165 offset:34816
	ds_read_b128 v[214:217], v165 offset:35840
	ds_read_b128 v[218:221], v165 offset:36864
	ds_read_b128 v[222:225], v165 offset:37888
	ds_read_b128 v[226:229], v165 offset:38912
	ds_read_b128 v[230:233], v165 offset:39936
	global_load_lds_dwordx4 v[238:239], off
	v_lshl_add_u64 v[238:239], s[24:25], 0, v[138:139]
	s_mov_b32 m0, s28
	s_nop 0
	global_load_lds_dwordx4 v[238:239], off
	s_waitcnt vmcnt(8)
	s_waitcnt lgkmcnt(0)
	s_barrier
	s_setprio 1
	s_waitcnt lgkmcnt(0)
	v_mfma_f32_16x16x32_bf16 v[132:135], v[104:107], v[202:205], v[132:135]
	v_mfma_f32_16x16x32_bf16 v[128:131], v[156:159], v[202:205], v[128:131]
	v_mfma_f32_16x16x32_bf16 v[124:127], v[104:107], v[210:213], v[124:127]
	v_mfma_f32_16x16x32_bf16 v[120:123], v[156:159], v[210:213], v[120:123]
	v_mfma_f32_16x16x32_bf16 v[116:119], v[104:107], v[218:221], v[116:119]
	v_mfma_f32_16x16x32_bf16 v[112:115], v[156:159], v[218:221], v[112:115]
	v_mfma_f32_16x16x32_bf16 v[100:103], v[104:107], v[226:229], v[100:103]
	v_mfma_f32_16x16x32_bf16 v[96:99], v[156:159], v[226:229], v[96:99]
	v_mfma_f32_16x16x32_bf16 v[132:135], v[108:111], v[206:209], v[132:135]
	v_mfma_f32_16x16x32_bf16 v[128:131], v[166:169], v[206:209], v[128:131]
	v_mfma_f32_16x16x32_bf16 v[124:127], v[108:111], v[214:217], v[124:127]
	v_mfma_f32_16x16x32_bf16 v[120:123], v[166:169], v[214:217], v[120:123]
	v_mfma_f32_16x16x32_bf16 v[116:119], v[108:111], v[222:225], v[116:119]
	v_mfma_f32_16x16x32_bf16 v[112:115], v[166:169], v[222:225], v[112:115]
	v_mfma_f32_16x16x32_bf16 v[100:103], v[108:111], v[230:233], v[100:103]
	v_mfma_f32_16x16x32_bf16 v[96:99], v[166:169], v[230:233], v[96:99]
	s_setprio 0
	s_setprio 1
	v_mfma_f32_16x16x32_bf16 v[60:63], v[186:189], v[202:205], v[60:63]
	v_mfma_f32_16x16x32_bf16 v[56:59], v[194:197], v[202:205], v[56:59]
	v_mfma_f32_16x16x32_bf16 v[52:55], v[186:189], v[210:213], v[52:55]
	v_mfma_f32_16x16x32_bf16 v[48:51], v[194:197], v[210:213], v[48:51]
	v_mfma_f32_16x16x32_bf16 v[44:47], v[186:189], v[218:221], v[44:47]
	v_mfma_f32_16x16x32_bf16 v[40:43], v[194:197], v[218:221], v[40:43]
	v_mfma_f32_16x16x32_bf16 v[36:39], v[186:189], v[226:229], v[36:39]
	v_mfma_f32_16x16x32_bf16 v[32:35], v[194:197], v[226:229], v[32:35]
	v_mfma_f32_16x16x32_bf16 v[60:63], v[190:193], v[206:209], v[60:63]
	v_mfma_f32_16x16x32_bf16 v[56:59], v[198:201], v[206:209], v[56:59]
	v_mfma_f32_16x16x32_bf16 v[52:55], v[190:193], v[214:217], v[52:55]
	v_mfma_f32_16x16x32_bf16 v[48:51], v[198:201], v[214:217], v[48:51]
	v_mfma_f32_16x16x32_bf16 v[44:47], v[190:193], v[222:225], v[44:47]
	v_mfma_f32_16x16x32_bf16 v[40:43], v[198:201], v[222:225], v[40:43]
	v_mfma_f32_16x16x32_bf16 v[36:39], v[190:193], v[230:233], v[36:39]
	v_mfma_f32_16x16x32_bf16 v[32:35], v[198:201], v[230:233], v[32:35]
	s_setprio 0
	s_barrier
	s_add_i32 s24, s62, s4
	v_lshl_add_u64 v[160:161], v[160:161], 0, s[68:69]
	s_mov_b32 m0, s24
	ds_read_b128 v[202:205], v165 offset:49152
	ds_read_b128 v[206:209], v165 offset:50176
	ds_read_b128 v[210:213], v165 offset:51200
	ds_read_b128 v[214:217], v165 offset:52224
	ds_read_b128 v[218:221], v165 offset:53248
	ds_read_b128 v[222:225], v165 offset:54272
	ds_read_b128 v[226:229], v165 offset:55296
	ds_read_b128 v[230:233], v165 offset:56320
	global_load_lds_dwordx4 v[160:161], off
	s_add_i32 m0, s24, 0x2000
	s_add_u32 s22, s22, 0x200080
	v_lshl_add_u64 v[160:161], v[170:171], 0, s[68:69]
	s_addc_u32 s23, s23, 0
	s_add_i32 s24, s63, s4
	global_load_lds_dwordx4 v[160:161], off
	v_lshl_add_u64 v[160:161], s[22:23], 0, v[140:141]
	s_mov_b32 m0, s24
	s_nop 0
	global_load_lds_dwordx4 v[160:161], off
	v_lshl_add_u64 v[160:161], s[22:23], 0, v[136:137]
	s_add_i32 m0, s24, 0x2000
	s_nop 0
	global_load_lds_dwordx4 v[160:161], off
	v_lshl_add_u64 v[160:161], v[234:235], 0, s[68:69]
	s_mov_b32 m0, s50
	s_nop 0
	global_load_lds_dwordx4 v[160:161], off
	v_lshl_add_u64 v[160:161], v[236:237], 0, s[68:69]
	s_mov_b32 m0, s51
	s_nop 0
	global_load_lds_dwordx4 v[160:161], off
	s_waitcnt vmcnt(8)
	s_waitcnt lgkmcnt(0)
	s_barrier
	s_setprio 1
	s_waitcnt lgkmcnt(0)
	v_mfma_f32_16x16x32_bf16 v[92:95], v[104:107], v[202:205], v[92:95]
	v_mfma_f32_16x16x32_bf16 v[88:91], v[156:159], v[202:205], v[88:91]
	v_mfma_f32_16x16x32_bf16 v[84:87], v[104:107], v[210:213], v[84:87]
	v_mfma_f32_16x16x32_bf16 v[80:83], v[156:159], v[210:213], v[80:83]
	v_mfma_f32_16x16x32_bf16 v[76:79], v[104:107], v[218:221], v[76:79]
	v_mfma_f32_16x16x32_bf16 v[72:75], v[156:159], v[218:221], v[72:75]
	v_mfma_f32_16x16x32_bf16 v[68:71], v[104:107], v[226:229], v[68:71]
	v_mfma_f32_16x16x32_bf16 v[64:67], v[156:159], v[226:229], v[64:67]
	v_mfma_f32_16x16x32_bf16 v[92:95], v[108:111], v[206:209], v[92:95]
	v_mfma_f32_16x16x32_bf16 v[88:91], v[166:169], v[206:209], v[88:91]
	v_mfma_f32_16x16x32_bf16 v[84:87], v[108:111], v[214:217], v[84:87]
	v_mfma_f32_16x16x32_bf16 v[80:83], v[166:169], v[214:217], v[80:83]
	v_mfma_f32_16x16x32_bf16 v[76:79], v[108:111], v[222:225], v[76:79]
	v_mfma_f32_16x16x32_bf16 v[72:75], v[166:169], v[222:225], v[72:75]
	v_mfma_f32_16x16x32_bf16 v[68:71], v[108:111], v[230:233], v[68:71]
	v_mfma_f32_16x16x32_bf16 v[64:67], v[166:169], v[230:233], v[64:67]
	s_setprio 0
	s_setprio 1
	v_mfma_f32_16x16x32_bf16 v[28:31], v[186:189], v[202:205], v[28:31]
	v_mfma_f32_16x16x32_bf16 v[24:27], v[194:197], v[202:205], v[24:27]
	v_mfma_f32_16x16x32_bf16 v[20:23], v[186:189], v[210:213], v[20:23]
	v_mfma_f32_16x16x32_bf16 v[16:19], v[194:197], v[210:213], v[16:19]
	v_mfma_f32_16x16x32_bf16 v[12:15], v[186:189], v[218:221], v[12:15]
	v_mfma_f32_16x16x32_bf16 v[8:11], v[194:197], v[218:221], v[8:11]
	v_mfma_f32_16x16x32_bf16 v[4:7], v[186:189], v[226:229], v[4:7]
	v_mfma_f32_16x16x32_bf16 v[0:3], v[194:197], v[226:229], v[0:3]
	v_mfma_f32_16x16x32_bf16 v[28:31], v[190:193], v[206:209], v[28:31]
	v_mfma_f32_16x16x32_bf16 v[24:27], v[198:201], v[206:209], v[24:27]
	v_mfma_f32_16x16x32_bf16 v[20:23], v[190:193], v[214:217], v[20:23]
	v_mfma_f32_16x16x32_bf16 v[16:19], v[198:201], v[214:217], v[16:19]
	v_mfma_f32_16x16x32_bf16 v[12:15], v[190:193], v[222:225], v[12:15]
	v_mfma_f32_16x16x32_bf16 v[8:11], v[198:201], v[222:225], v[8:11]
	v_mfma_f32_16x16x32_bf16 v[4:7], v[190:193], v[230:233], v[4:7]
	v_mfma_f32_16x16x32_bf16 v[0:3], v[198:201], v[230:233], v[0:3]
	s_setprio 0
	s_barrier
	s_add_i32 s22, s61, 2
	s_add_u32 s20, s20, 0x100
	s_addc_u32 s21, s21, 0
	s_add_u32 s58, s58, 0x100
	s_addc_u32 s60, s60, 0
	s_cmp_ge_u32 s61, s39
	s_mov_b32 s61, s22
	s_cbranch_scc0 .LBB0_1057
	s_and_b64 vcc, exec, s[14:15]
	s_cbranch_vccz .LBB0_1060
	s_barrier
